# kernel start: grid-sync workspace pointer loaded with the kernargs at entry instead of inside the grid sync
# baseline (speedup 1.0000x reference)
; #define LAS __attribute__((address_space(3)))
; __global__ void __launch_bounds__(512) fwd_kernel(Args a) {
;     ...
;     const int tid = threadIdx.x, lane = tid & 63, wave = __builtin_amdgcn_readfirstlane(tid >> 6);
;     const int G = gridDim.x, gw = blockIdx.x * 8 + wave, NGW = G * 8;
;     cg::grid_group grid = cg::this_grid();
;     volatile LAS unsigned* xst = (volatile LAS unsigned*)(lds + LDS_BYTES - 16);
;     if (tid < 4) xst[tid] = 0u;
;     __syncthreads();
;     if (a.ph_lo == 0) { if (blockIdx.x == 0) for (int i = tid; i < XCD_BAR_WORDS; i += 512) ((unsigned*)(a.ws + WS_BAR))[i] = 0u;
;         grid.sync(); (void)xcd_barrier_post((unsigned*)(a.ws + WS_BAR), xst); }
_Z10fwd_kernel4Args:
	s_load_dwordx8 s[52:59], s[0:1], 0xa0
	s_load_dwordx8 s[60:67], s[0:1], 0x80
	s_load_dword s3, s[0:1], 0xc0
	v_and_b32_e32 v178, 0x3ff, v0
	s_add_u32 s6, s0, 0xb8
	v_readfirstlane_b32 s94, v178
	s_addc_u32 s7, s1, 0
	s_load_dwordx2 s[100:101], s[6:7], 0x58
	v_cmp_gt_u32_e32 vcc, 4, v178
	s_waitcnt lgkmcnt(0)
	v_writelane_b32 v252, s3, 0
	s_and_saveexec_b64 s[4:5], vcc
	v_lshl_add_u32 v1, v178, 2, 0
	v_add_u32_e32 v1, 0x23ff0, v1
	v_mov_b32_e32 v2, 0
	ds_write_b32 v1, v2
	s_or_b64 exec, exec, s[4:5]
	s_load_dwordx16 s[8:23], s[0:1], 0x0
	s_cmp_lg_u32 s56, 0
	s_waitcnt lgkmcnt(0)
	s_barrier
	v_writelane_b32 v252, s8, 1
	s_nop 1
	v_writelane_b32 v252, s9, 2
	v_writelane_b32 v252, s10, 3
	v_writelane_b32 v252, s11, 4
	v_writelane_b32 v252, s12, 5
	v_writelane_b32 v252, s13, 6
	v_writelane_b32 v252, s14, 7
	v_writelane_b32 v252, s15, 8
	v_writelane_b32 v252, s16, 9
	v_writelane_b32 v252, s17, 10
	v_writelane_b32 v252, s18, 11
	v_writelane_b32 v252, s19, 12
	v_writelane_b32 v252, s20, 13
	v_writelane_b32 v252, s21, 14
	v_writelane_b32 v252, s22, 15
	v_writelane_b32 v252, s23, 16
	s_cbranch_scc1 .LBB0_25
	s_cmp_lg_u32 s2, 0
	s_cbranch_scc1 .LBB0_11
	s_add_u32 s8, s54, 0x22a2000
	s_addc_u32 s9, s55, 0
	v_lshlrev_b32_e32 v1, 4, v178
	v_mov_b32_e32 v4, 0
	v_mov_b32_e32 v5, 0
	v_mov_b32_e32 v6, 0
	v_mov_b32_e32 v7, 0
	global_store_dwordx4 v1, v[4:7], s[8:9]
	v_cmp_gt_u32_e32 vcc, 0x160, v178
	s_add_u32 s10, s8, 0x2000
	s_addc_u32 s11, s9, 0
	s_and_saveexec_b64 s[12:13], vcc
	global_store_dwordx4 v1, v[4:7], s[10:11]

; __global__ void __launch_bounds__(512) fwd_kernel(Args a) {
;     ...
;     if (a.ph_lo == 0) { if (blockIdx.x == 0) for (int i = tid; i < XCD_BAR_WORDS; i += 512) ((unsigned*)(a.ws + WS_BAR))[i] = 0u;
;         grid.sync(); (void)xcd_barrier_post((unsigned*)(a.ws + WS_BAR), xst); }
.Lstart_nowb:
	s_waitcnt vmcnt(0)
	v_mov_b32_e32 v2, 0
	s_mov_b64 s[8:9], exec
	v_mbcnt_lo_u32_b32 v1, s8, 0
	v_mbcnt_hi_u32_b32 v1, s9, v1
	s_waitcnt lgkmcnt(0)
	global_load_dword v0, v2, s[100:101] offset:40
	v_cmp_eq_u32_e32 vcc, 0, v1
	s_and_saveexec_b64 s[10:11], vcc
	s_cbranch_execz .LBB0_14
	s_bcnt1_i32_b64 s3, s[8:9]
	v_mov_b32_e32 v3, s3
	global_atomic_add v3, v2, v3, s[100:101] offset:32 sc0
.LBB0_14:
	s_or_b64 exec, exec, s[10:11]
	s_waitcnt vmcnt(0)
	v_readfirstlane_b32 s3, v3
	v_add_u32_e32 v2, -1, v0
	s_nop 0
	v_add_u32_e32 v1, s3, v1
	v_cmp_eq_u32_sdwa s[10:11], v1, v2 src0_sel:WORD_0 src1_sel:DWORD
	s_and_saveexec_b64 s[8:9], s[10:11]
	s_cbranch_execz .LBB0_17
	s_mov_b64 s[10:11], exec
	v_mbcnt_lo_u32_b32 v2, s10, 0
	v_mbcnt_hi_u32_b32 v2, s11, v2
	v_cmp_eq_u32_e32 vcc, 0, v2
	s_and_b64 s[12:13], exec, vcc
	s_mov_b64 exec, s[12:13]
	s_cbranch_execz .LBB0_17
	v_sub_u32_e32 v0, 0x10000, v0
	s_bcnt1_i32_b64 s3, s[10:11]
	v_mul_lo_u32 v0, v0, s3
	v_mov_b32_e32 v2, 0
	global_atomic_add v2, v0, s[100:101] offset:32
.LBB0_17:
	s_or_b64 exec, exec, s[8:9]
	v_mov_b32_e32 v0, 0
	global_load_dword v2, v0, s[100:101] offset:32 sc1
	v_and_b32_e32 v1, 0xffff0000, v1
	s_waitcnt vmcnt(0)
	v_and_b32_e32 v2, 0xffff0000, v2
	v_cmp_eq_u32_e32 vcc, v2, v1
	s_and_b64 exec, exec, vcc
	s_cbranch_execz .LBB0_20
	s_mov_b64 s[8:9], 0
.LBB0_19:
	s_sleep 1
	global_load_dword v2, v0, s[100:101] offset:32 sc1
	s_waitcnt vmcnt(0)
	v_and_b32_e32 v2, 0xffff0000, v2
	v_cmp_ne_u32_e32 vcc, v2, v1
	s_or_b64 s[8:9], vcc, s[8:9]
	s_andn2_b64 exec, exec, s[8:9]
	s_cbranch_execnz .LBB0_19
